# all four GEMM K-loops: LDS-DMA loads in saddr form
# speedup vs baseline: 1.0115x; 1.0007x over previous
.LBB0_365:
	s_add_u32 s10, s60, s8
	s_addc_u32 s11, s61, s9
	s_add_u32 s10, s10, 0x5dc0100
	s_addc_u32 s11, s11, 0
	s_add_u32 s65, s62, s8
	s_addc_u32 s66, s63, s9
	s_add_i32 s67, 0, 0x10000
	s_cmpk_eq_i32 s8, 0x700
	s_cselect_b32 s27, s7, s11
	s_cselect_b32 s26, s6, s10
	s_cselect_b32 s11, s1, s66
	s_cselect_b32 s10, s0, s65
	s_add_i32 s65, 0, 0x14000
	v_add_u32_e32 v144, s67, v122
	v_add_u32_e32 v165, s65, v122
	ds_read_b128 v[124:127], v144
	ds_read_b128 v[128:131], v144 offset:1024
	ds_read_b128 v[132:135], v144 offset:2048
	ds_read_b128 v[144:147], v144 offset:3072
	ds_read_b128 v[148:151], v165
	ds_read_b128 v[160:163], v165 offset:1024
	ds_read_b128 v[166:169], v165 offset:2048
	ds_read_b128 v[170:173], v165 offset:3072
	v_lshl_add_u64 v[206:207], v[110:111], 0, s[8:9]
	s_add_i32 m0, s23, 0xc000
	ds_read_b128 v[174:177], v123
	ds_read_b128 v[178:181], v123 offset:1024
	ds_read_b128 v[182:185], v123 offset:2048
	ds_read_b128 v[186:189], v123 offset:3072
	ds_read_b128 v[190:193], v123 offset:4096
	ds_read_b128 v[194:197], v123 offset:5120
	ds_read_b128 v[198:201], v123 offset:6144
	ds_read_b128 v[202:205], v123 offset:7168
	global_load_lds_dwordx4 v[206:207], off
	v_lshl_add_u64 v[206:207], v[120:121], 0, s[8:9]
	s_add_i32 m0, s23, 0xe000
	s_nop 0
	global_load_lds_dwordx4 v[206:207], off
	s_waitcnt vmcnt(8)
	s_waitcnt lgkmcnt(0)
	s_barrier
	s_setprio 1
	s_waitcnt lgkmcnt(0)
	v_mfma_f32_16x16x32_bf16 v[156:159], v[124:127], v[174:177], v[156:159]
	v_mfma_f32_16x16x32_bf16 v[152:155], v[132:135], v[174:177], v[152:155]
	v_mfma_f32_16x16x32_bf16 v[116:119], v[124:127], v[182:185], v[116:119]
	v_mfma_f32_16x16x32_bf16 v[112:115], v[132:135], v[182:185], v[112:115]
	v_mfma_f32_16x16x32_bf16 v[92:95], v[124:127], v[190:193], v[92:95]
	v_mfma_f32_16x16x32_bf16 v[88:91], v[132:135], v[190:193], v[88:91]
	v_mfma_f32_16x16x32_bf16 v[76:79], v[124:127], v[198:201], v[76:79]
	v_mfma_f32_16x16x32_bf16 v[72:75], v[132:135], v[198:201], v[72:75]
	v_mfma_f32_16x16x32_bf16 v[156:159], v[128:131], v[178:181], v[156:159]
	v_mfma_f32_16x16x32_bf16 v[152:155], v[144:147], v[178:181], v[152:155]
	v_mfma_f32_16x16x32_bf16 v[116:119], v[128:131], v[186:189], v[116:119]
	v_mfma_f32_16x16x32_bf16 v[112:115], v[144:147], v[186:189], v[112:115]
	v_mfma_f32_16x16x32_bf16 v[92:95], v[128:131], v[194:197], v[92:95]
	v_mfma_f32_16x16x32_bf16 v[88:91], v[144:147], v[194:197], v[88:91]
	v_mfma_f32_16x16x32_bf16 v[76:79], v[128:131], v[202:205], v[76:79]
	v_mfma_f32_16x16x32_bf16 v[72:75], v[144:147], v[202:205], v[72:75]
	s_setprio 0
	s_setprio 1
	v_mfma_f32_16x16x32_bf16 v[140:143], v[148:151], v[174:177], v[140:143]
	v_mfma_f32_16x16x32_bf16 v[136:139], v[166:169], v[174:177], v[136:139]
	v_mfma_f32_16x16x32_bf16 v[104:107], v[148:151], v[182:185], v[104:107]
	v_mfma_f32_16x16x32_bf16 v[96:99], v[166:169], v[182:185], v[96:99]
	v_mfma_f32_16x16x32_bf16 v[84:87], v[148:151], v[190:193], v[84:87]
	v_mfma_f32_16x16x32_bf16 v[80:83], v[166:169], v[190:193], v[80:83]
	v_mfma_f32_16x16x32_bf16 v[68:71], v[148:151], v[198:201], v[68:71]
	v_mfma_f32_16x16x32_bf16 v[64:67], v[166:169], v[198:201], v[64:67]
	v_mfma_f32_16x16x32_bf16 v[140:143], v[160:163], v[178:181], v[140:143]
	v_mfma_f32_16x16x32_bf16 v[136:139], v[170:173], v[178:181], v[136:139]
	v_mfma_f32_16x16x32_bf16 v[104:107], v[160:163], v[186:189], v[104:107]
	v_mfma_f32_16x16x32_bf16 v[96:99], v[170:173], v[186:189], v[96:99]
	v_mfma_f32_16x16x32_bf16 v[84:87], v[160:163], v[194:197], v[84:87]
	v_mfma_f32_16x16x32_bf16 v[80:83], v[170:173], v[194:197], v[80:83]
	v_mfma_f32_16x16x32_bf16 v[68:71], v[160:163], v[202:205], v[68:71]
	v_mfma_f32_16x16x32_bf16 v[64:67], v[170:173], v[202:205], v[64:67]
	s_setprio 0
	s_barrier
	s_add_i32 s66, s67, s48
	s_mov_b32 m0, s66
	ds_read_b128 v[174:177], v123 offset:16384
	ds_read_b128 v[178:181], v123 offset:17408
	ds_read_b128 v[182:185], v123 offset:18432
	ds_read_b128 v[186:189], v123 offset:19456
	ds_read_b128 v[190:193], v123 offset:20480
	ds_read_b128 v[194:197], v123 offset:21504
	ds_read_b128 v[198:201], v123 offset:22528
	ds_read_b128 v[202:205], v123 offset:23552
	global_load_lds_dwordx4 v212, s[10:11]
	s_add_i32 m0, s66, 0x2000
	s_add_u32 s66, s10, 0x40000
	s_addc_u32 s67, s11, 0
	s_add_i32 s65, s65, s48
	global_load_lds_dwordx4 v100, s[10:11]
	s_mov_b32 m0, s65
	s_nop 0
	global_load_lds_dwordx4 v212, s[66:67]
	s_add_i32 m0, s65, 0x2000
	s_nop 0
	global_load_lds_dwordx4 v100, s[66:67]
	s_mov_b32 m0, s23
	s_nop 0
	global_load_lds_dwordx4 v108, s[26:27]
	s_mov_b32 m0, s49
	s_nop 0
	global_load_lds_dwordx4 v102, s[26:27]
	s_add_u32 s86, s26, s34
	s_addc_u32 s87, s27, s35
	s_add_u32 s84, s10, s34
	s_addc_u32 s85, s11, s35
	s_waitcnt vmcnt(8)
	s_waitcnt lgkmcnt(0)
	s_barrier
	s_setprio 1
	s_waitcnt lgkmcnt(0)
	v_mfma_f32_16x16x32_bf16 v[60:63], v[124:127], v[174:177], v[60:63]
	v_mfma_f32_16x16x32_bf16 v[56:59], v[132:135], v[174:177], v[56:59]
	v_mfma_f32_16x16x32_bf16 v[44:47], v[124:127], v[182:185], v[44:47]
	v_mfma_f32_16x16x32_bf16 v[40:43], v[132:135], v[182:185], v[40:43]
	v_mfma_f32_16x16x32_bf16 v[28:31], v[124:127], v[190:193], v[28:31]
	v_mfma_f32_16x16x32_bf16 v[24:27], v[132:135], v[190:193], v[24:27]
	v_mfma_f32_16x16x32_bf16 v[12:15], v[124:127], v[198:201], v[12:15]
	v_mfma_f32_16x16x32_bf16 v[8:11], v[132:135], v[198:201], v[8:11]
	v_mfma_f32_16x16x32_bf16 v[60:63], v[128:131], v[178:181], v[60:63]
	v_mfma_f32_16x16x32_bf16 v[56:59], v[144:147], v[178:181], v[56:59]
	v_mfma_f32_16x16x32_bf16 v[44:47], v[128:131], v[186:189], v[44:47]
	v_mfma_f32_16x16x32_bf16 v[40:43], v[144:147], v[186:189], v[40:43]
	v_mfma_f32_16x16x32_bf16 v[28:31], v[128:131], v[194:197], v[28:31]
	v_mfma_f32_16x16x32_bf16 v[24:27], v[144:147], v[194:197], v[24:27]
	v_mfma_f32_16x16x32_bf16 v[12:15], v[128:131], v[202:205], v[12:15]
	v_mfma_f32_16x16x32_bf16 v[8:11], v[144:147], v[202:205], v[8:11]
	s_setprio 0
	s_setprio 1
	v_mfma_f32_16x16x32_bf16 v[52:55], v[148:151], v[174:177], v[52:55]
	v_mfma_f32_16x16x32_bf16 v[48:51], v[166:169], v[174:177], v[48:51]
	v_mfma_f32_16x16x32_bf16 v[36:39], v[148:151], v[182:185], v[36:39]
	v_mfma_f32_16x16x32_bf16 v[32:35], v[166:169], v[182:185], v[32:35]
	v_mfma_f32_16x16x32_bf16 v[20:23], v[148:151], v[190:193], v[20:23]
	v_mfma_f32_16x16x32_bf16 v[16:19], v[166:169], v[190:193], v[16:19]
	v_mfma_f32_16x16x32_bf16 v[4:7], v[148:151], v[198:201], v[4:7]
	v_mfma_f32_16x16x32_bf16 v[0:3], v[166:169], v[198:201], v[0:3]
	v_mfma_f32_16x16x32_bf16 v[52:55], v[160:163], v[178:181], v[52:55]
	v_mfma_f32_16x16x32_bf16 v[48:51], v[170:173], v[178:181], v[48:51]
	v_mfma_f32_16x16x32_bf16 v[36:39], v[160:163], v[186:189], v[36:39]
	v_mfma_f32_16x16x32_bf16 v[32:35], v[170:173], v[186:189], v[32:35]
	v_mfma_f32_16x16x32_bf16 v[20:23], v[160:163], v[194:197], v[20:23]
	v_mfma_f32_16x16x32_bf16 v[16:19], v[170:173], v[194:197], v[16:19]
	v_mfma_f32_16x16x32_bf16 v[4:7], v[160:163], v[202:205], v[4:7]
	v_mfma_f32_16x16x32_bf16 v[0:3], v[170:173], v[202:205], v[0:3]
	s_setprio 0
	s_barrier
	s_add_i32 s65, 0, 0x18000
	s_add_i32 s66, 0, 0x1c000
	v_add_u32_e32 v144, s65, v122
	v_add_u32_e32 v165, s66, v122
	ds_read_b128 v[124:127], v144
	ds_read_b128 v[128:131], v144 offset:1024
	ds_read_b128 v[132:135], v144 offset:2048
	ds_read_b128 v[144:147], v144 offset:3072
	ds_read_b128 v[148:151], v165
	ds_read_b128 v[160:163], v165 offset:1024
	ds_read_b128 v[166:169], v165 offset:2048
	ds_read_b128 v[170:173], v165 offset:3072
	s_add_u32 s26, s26, 0x40000
	s_addc_u32 s27, s27, 0
	s_mov_b32 m0, s50
	ds_read_b128 v[174:177], v123 offset:32768
	ds_read_b128 v[178:181], v123 offset:33792
	ds_read_b128 v[182:185], v123 offset:34816
	ds_read_b128 v[186:189], v123 offset:35840
	ds_read_b128 v[190:193], v123 offset:36864
	ds_read_b128 v[194:197], v123 offset:37888
	ds_read_b128 v[198:201], v123 offset:38912
	ds_read_b128 v[202:205], v123 offset:39936
	global_load_lds_dwordx4 v108, s[26:27]
	s_mov_b32 m0, s51
	s_nop 0
	global_load_lds_dwordx4 v102, s[26:27]
	s_waitcnt vmcnt(8)
	s_waitcnt lgkmcnt(0)
	s_barrier
	s_setprio 1
	s_waitcnt lgkmcnt(0)
	v_mfma_f32_16x16x32_bf16 v[156:159], v[124:127], v[174:177], v[156:159]
	v_mfma_f32_16x16x32_bf16 v[152:155], v[132:135], v[174:177], v[152:155]
	v_mfma_f32_16x16x32_bf16 v[116:119], v[124:127], v[182:185], v[116:119]
	v_mfma_f32_16x16x32_bf16 v[112:115], v[132:135], v[182:185], v[112:115]
	v_mfma_f32_16x16x32_bf16 v[92:95], v[124:127], v[190:193], v[92:95]
	v_mfma_f32_16x16x32_bf16 v[88:91], v[132:135], v[190:193], v[88:91]
	v_mfma_f32_16x16x32_bf16 v[76:79], v[124:127], v[198:201], v[76:79]
	v_mfma_f32_16x16x32_bf16 v[72:75], v[132:135], v[198:201], v[72:75]
	v_mfma_f32_16x16x32_bf16 v[156:159], v[128:131], v[178:181], v[156:159]
	v_mfma_f32_16x16x32_bf16 v[152:155], v[144:147], v[178:181], v[152:155]
	v_mfma_f32_16x16x32_bf16 v[116:119], v[128:131], v[186:189], v[116:119]
	v_mfma_f32_16x16x32_bf16 v[112:115], v[144:147], v[186:189], v[112:115]
	v_mfma_f32_16x16x32_bf16 v[92:95], v[128:131], v[194:197], v[92:95]
	v_mfma_f32_16x16x32_bf16 v[88:91], v[144:147], v[194:197], v[88:91]
	v_mfma_f32_16x16x32_bf16 v[76:79], v[128:131], v[202:205], v[76:79]
	v_mfma_f32_16x16x32_bf16 v[72:75], v[144:147], v[202:205], v[72:75]
	s_setprio 0
	s_setprio 1
	v_mfma_f32_16x16x32_bf16 v[140:143], v[148:151], v[174:177], v[140:143]
	v_mfma_f32_16x16x32_bf16 v[136:139], v[166:169], v[174:177], v[136:139]
	v_mfma_f32_16x16x32_bf16 v[104:107], v[148:151], v[182:185], v[104:107]
	v_mfma_f32_16x16x32_bf16 v[96:99], v[166:169], v[182:185], v[96:99]
	v_mfma_f32_16x16x32_bf16 v[84:87], v[148:151], v[190:193], v[84:87]
	v_mfma_f32_16x16x32_bf16 v[80:83], v[166:169], v[190:193], v[80:83]
	v_mfma_f32_16x16x32_bf16 v[68:71], v[148:151], v[198:201], v[68:71]
	v_mfma_f32_16x16x32_bf16 v[64:67], v[166:169], v[198:201], v[64:67]
	v_mfma_f32_16x16x32_bf16 v[140:143], v[160:163], v[178:181], v[140:143]
	v_mfma_f32_16x16x32_bf16 v[136:139], v[170:173], v[178:181], v[136:139]
	v_mfma_f32_16x16x32_bf16 v[104:107], v[160:163], v[186:189], v[104:107]
	v_mfma_f32_16x16x32_bf16 v[96:99], v[170:173], v[186:189], v[96:99]
	v_mfma_f32_16x16x32_bf16 v[84:87], v[160:163], v[194:197], v[84:87]
	v_mfma_f32_16x16x32_bf16 v[80:83], v[170:173], v[194:197], v[80:83]
	v_mfma_f32_16x16x32_bf16 v[68:71], v[160:163], v[202:205], v[68:71]
	v_mfma_f32_16x16x32_bf16 v[64:67], v[170:173], v[202:205], v[64:67]
	s_setprio 0
	s_barrier
	s_add_i32 s26, s65, s48
	s_mov_b32 m0, s26
	ds_read_b128 v[174:177], v123 offset:49152
	ds_read_b128 v[178:181], v123 offset:50176
	ds_read_b128 v[182:185], v123 offset:51200
	ds_read_b128 v[186:189], v123 offset:52224
	ds_read_b128 v[190:193], v123 offset:53248
	ds_read_b128 v[194:197], v123 offset:54272
	ds_read_b128 v[198:201], v123 offset:55296
	ds_read_b128 v[202:205], v123 offset:56320
	global_load_lds_dwordx4 v212, s[84:85]
	s_add_i32 m0, s26, 0x2000
	s_add_u32 s10, s10, 0x40080
	s_addc_u32 s11, s11, 0
	s_add_i32 s26, s66, s48
	global_load_lds_dwordx4 v100, s[84:85]
	s_mov_b32 m0, s26
	s_nop 0
	global_load_lds_dwordx4 v212, s[10:11]
	s_add_i32 m0, s26, 0x2000
	s_nop 0
	global_load_lds_dwordx4 v100, s[10:11]
	s_mov_b32 m0, s58
	s_nop 0
	global_load_lds_dwordx4 v108, s[86:87]
	s_mov_b32 m0, s59
	s_nop 0
	global_load_lds_dwordx4 v102, s[86:87]
	s_waitcnt vmcnt(8)
	s_waitcnt lgkmcnt(0)
	s_barrier
	s_setprio 1
	s_waitcnt lgkmcnt(0)
	v_mfma_f32_16x16x32_bf16 v[60:63], v[124:127], v[174:177], v[60:63]
	v_mfma_f32_16x16x32_bf16 v[56:59], v[132:135], v[174:177], v[56:59]
	v_mfma_f32_16x16x32_bf16 v[44:47], v[124:127], v[182:185], v[44:47]
	v_mfma_f32_16x16x32_bf16 v[40:43], v[132:135], v[182:185], v[40:43]
	v_mfma_f32_16x16x32_bf16 v[28:31], v[124:127], v[190:193], v[28:31]
	v_mfma_f32_16x16x32_bf16 v[24:27], v[132:135], v[190:193], v[24:27]
	v_mfma_f32_16x16x32_bf16 v[12:15], v[124:127], v[198:201], v[12:15]
	v_mfma_f32_16x16x32_bf16 v[8:11], v[132:135], v[198:201], v[8:11]
	v_mfma_f32_16x16x32_bf16 v[60:63], v[128:131], v[178:181], v[60:63]
	v_mfma_f32_16x16x32_bf16 v[56:59], v[144:147], v[178:181], v[56:59]
	v_mfma_f32_16x16x32_bf16 v[44:47], v[128:131], v[186:189], v[44:47]
	v_mfma_f32_16x16x32_bf16 v[40:43], v[144:147], v[186:189], v[40:43]
	v_mfma_f32_16x16x32_bf16 v[28:31], v[128:131], v[194:197], v[28:31]
	v_mfma_f32_16x16x32_bf16 v[24:27], v[144:147], v[194:197], v[24:27]
	v_mfma_f32_16x16x32_bf16 v[12:15], v[128:131], v[202:205], v[12:15]
	v_mfma_f32_16x16x32_bf16 v[8:11], v[144:147], v[202:205], v[8:11]
	s_setprio 0
	s_setprio 1
	v_mfma_f32_16x16x32_bf16 v[52:55], v[148:151], v[174:177], v[52:55]
	v_mfma_f32_16x16x32_bf16 v[48:51], v[166:169], v[174:177], v[48:51]
	v_mfma_f32_16x16x32_bf16 v[36:39], v[148:151], v[182:185], v[36:39]
	v_mfma_f32_16x16x32_bf16 v[32:35], v[166:169], v[182:185], v[32:35]
	v_mfma_f32_16x16x32_bf16 v[20:23], v[148:151], v[190:193], v[20:23]
	v_mfma_f32_16x16x32_bf16 v[16:19], v[166:169], v[190:193], v[16:19]
	v_mfma_f32_16x16x32_bf16 v[4:7], v[148:151], v[198:201], v[4:7]
	v_mfma_f32_16x16x32_bf16 v[0:3], v[166:169], v[198:201], v[0:3]
	v_mfma_f32_16x16x32_bf16 v[52:55], v[160:163], v[178:181], v[52:55]
	v_mfma_f32_16x16x32_bf16 v[48:51], v[170:173], v[178:181], v[48:51]
	v_mfma_f32_16x16x32_bf16 v[36:39], v[160:163], v[186:189], v[36:39]
	v_mfma_f32_16x16x32_bf16 v[32:35], v[170:173], v[186:189], v[32:35]
	v_mfma_f32_16x16x32_bf16 v[20:23], v[160:163], v[194:197], v[20:23]
	v_mfma_f32_16x16x32_bf16 v[16:19], v[170:173], v[194:197], v[16:19]
	v_mfma_f32_16x16x32_bf16 v[4:7], v[160:163], v[202:205], v[4:7]
	v_mfma_f32_16x16x32_bf16 v[0:3], v[170:173], v[202:205], v[0:3]
	s_setprio 0
	s_barrier
	s_add_i32 s64, s64, 2
	s_add_u32 s8, s8, 0x100
	s_addc_u32 s9, s9, 0
	s_cmp_lt_u32 s64, 14
	s_cbranch_scc1 .LBB0_365
	s_waitcnt vmcnt(0)
	s_cmpk_gt_u32 s47, 0xff
	s_cbranch_scc1 .LBB0_368
	s_barrier

.LBB0_497:
	s_ashr_i32 s11, s10, 31
	s_lshl_b64 s[22:23], s[10:11], 19
	s_add_u32 s22, s16, s22
	s_addc_u32 s23, s17, s23
	s_and_b64 s[24:25], s[0:1], exec
	s_cselect_b32 s11, s23, s31
	s_cselect_b32 s49, s22, s30
	s_ashr_i32 s9, s8, 31
	s_lshl_b64 s[24:25], s[8:9], 19
	s_add_u32 s24, s33, s24
	s_addc_u32 s25, s34, s25
	s_and_b64 s[50:51], s[0:1], exec
	s_cselect_b32 s9, s25, s29
	s_cselect_b32 s50, s24, s28
	v_lshl_add_u32 v152, s26, 8, v164
	s_add_u32 s26, s30, 0x40080
	v_add_u32_e32 v150, 0x80, v152
	v_add_u32_e32 v148, 0x90, v152
	v_add_u32_e32 v146, 0xa0, v152
	v_add_u32_e32 v144, 0xb0, v152
	s_addc_u32 s27, s31, 0
	v_ashrrev_i32_e32 v153, 31, v152
	v_ashrrev_i32_e32 v151, 31, v150
	v_ashrrev_i32_e32 v149, 31, v148
	v_ashrrev_i32_e32 v147, 31, v146
	v_ashrrev_i32_e32 v145, 31, v144
	s_add_u32 s51, s28, 0x100
	v_lshl_add_u64 v[154:155], v[152:153], 2, s[20:21]
	v_lshl_add_u64 v[156:157], v[150:151], 2, s[20:21]
	v_lshl_add_u64 v[158:159], v[148:149], 2, s[20:21]
	v_lshl_add_u64 v[160:161], v[146:147], 2, s[20:21]
	v_lshl_add_u64 v[162:163], v[144:145], 2, s[20:21]
	s_addc_u32 s52, s29, 0
	s_mov_b32 s53, -2
	s_mov_b64 s[28:29], 0
	v_add_u32_e32 v188, s46, v165
	v_add_u32_e32 v204, s47, v165
	ds_read_b128 v[176:179], v188
	ds_read_b128 v[180:183], v188 offset:1024
	ds_read_b128 v[184:187], v188 offset:2048
	ds_read_b128 v[188:191], v188 offset:3072
	ds_read_b128 v[192:195], v204
	ds_read_b128 v[196:199], v204 offset:1024
	ds_read_b128 v[200:203], v204 offset:2048
	ds_read_b128 v[204:207], v204 offset:3072
	s_add_u32 s30, s26, 0xfffc0080
	s_addc_u32 s31, s27, -1
	s_and_b64 s[28:29], s[28:29], exec
	s_cselect_b32 s31, s11, s31
	s_cselect_b32 s30, s49, s30
	s_cselect_b32 s29, s9, s52
	s_cselect_b32 s28, s50, s51
	s_add_i32 m0, s36, 0xc000
	ds_read_b128 v[208:211], v167
	ds_read_b128 v[212:215], v167 offset:1024
	ds_read_b128 v[216:219], v167 offset:2048
	ds_read_b128 v[220:223], v167 offset:3072
	ds_read_b128 v[224:227], v167 offset:4096
	ds_read_b128 v[230:233], v167 offset:5120
	ds_read_b128 v[234:237], v167 offset:6144
	ds_read_b128 v[238:241], v167 offset:7168
	global_load_lds_dwordx4 v136, s[26:27]
	s_add_i32 m0, s36, 0xe000
	s_nop 0
	global_load_lds_dwordx4 v138, s[26:27]
	s_waitcnt vmcnt(8)
	s_waitcnt lgkmcnt(0)
	s_barrier
	s_setprio 1
	s_waitcnt lgkmcnt(0)
	v_mfma_f32_16x16x32_bf16 v[124:127], v[176:179], v[208:211], 0
	v_mfma_f32_16x16x32_bf16 v[120:123], v[184:187], v[208:211], 0
	v_mfma_f32_16x16x32_bf16 v[108:111], v[176:179], v[216:219], 0
	v_mfma_f32_16x16x32_bf16 v[104:107], v[184:187], v[216:219], 0
	v_mfma_f32_16x16x32_bf16 v[92:95], v[176:179], v[224:227], 0
	v_mfma_f32_16x16x32_bf16 v[88:91], v[184:187], v[224:227], 0
	v_mfma_f32_16x16x32_bf16 v[76:79], v[176:179], v[234:237], 0
	v_mfma_f32_16x16x32_bf16 v[72:75], v[184:187], v[234:237], 0
	v_mfma_f32_16x16x32_bf16 v[124:127], v[180:183], v[212:215], v[124:127]
	v_mfma_f32_16x16x32_bf16 v[120:123], v[188:191], v[212:215], v[120:123]
	v_mfma_f32_16x16x32_bf16 v[108:111], v[180:183], v[220:223], v[108:111]
	v_mfma_f32_16x16x32_bf16 v[104:107], v[188:191], v[220:223], v[104:107]
	v_mfma_f32_16x16x32_bf16 v[92:95], v[180:183], v[230:233], v[92:95]
	v_mfma_f32_16x16x32_bf16 v[88:91], v[188:191], v[230:233], v[88:91]
	v_mfma_f32_16x16x32_bf16 v[76:79], v[180:183], v[238:241], v[76:79]
	v_mfma_f32_16x16x32_bf16 v[72:75], v[188:191], v[238:241], v[72:75]
	s_setprio 0
	s_setprio 1
	v_mfma_f32_16x16x32_bf16 v[116:119], v[192:195], v[208:211], 0
	v_mfma_f32_16x16x32_bf16 v[112:115], v[200:203], v[208:211], 0
	v_mfma_f32_16x16x32_bf16 v[100:103], v[192:195], v[216:219], 0
	v_mfma_f32_16x16x32_bf16 v[96:99], v[200:203], v[216:219], 0
	v_mfma_f32_16x16x32_bf16 v[84:87], v[192:195], v[224:227], 0
	v_mfma_f32_16x16x32_bf16 v[80:83], v[200:203], v[224:227], 0
	v_mfma_f32_16x16x32_bf16 v[68:71], v[192:195], v[234:237], 0
	v_mfma_f32_16x16x32_bf16 v[64:67], v[200:203], v[234:237], 0
	v_mfma_f32_16x16x32_bf16 v[116:119], v[196:199], v[212:215], v[116:119]
	v_mfma_f32_16x16x32_bf16 v[112:115], v[204:207], v[212:215], v[112:115]
	v_mfma_f32_16x16x32_bf16 v[100:103], v[196:199], v[220:223], v[100:103]
	v_mfma_f32_16x16x32_bf16 v[96:99], v[204:207], v[220:223], v[96:99]
	v_mfma_f32_16x16x32_bf16 v[84:87], v[196:199], v[230:233], v[84:87]
	v_mfma_f32_16x16x32_bf16 v[80:83], v[204:207], v[230:233], v[80:83]
	v_mfma_f32_16x16x32_bf16 v[68:71], v[196:199], v[238:241], v[68:71]
	v_mfma_f32_16x16x32_bf16 v[64:67], v[204:207], v[238:241], v[64:67]
	s_setprio 0
	s_barrier
	s_add_i32 s54, s46, s35
	s_mov_b32 m0, s54
	ds_read_b128 v[208:211], v167 offset:16384
	ds_read_b128 v[212:215], v167 offset:17408
	ds_read_b128 v[216:219], v167 offset:18432
	ds_read_b128 v[220:223], v167 offset:19456
	ds_read_b128 v[224:227], v167 offset:20480
	ds_read_b128 v[230:233], v167 offset:21504
	ds_read_b128 v[234:237], v167 offset:22528
	ds_read_b128 v[238:241], v167 offset:23552
	global_load_lds_dwordx4 v130, s[28:29]
	s_add_i32 m0, s54, 0x2000
	s_add_u32 s54, s28, 0x40000
	s_addc_u32 s55, s29, 0
	s_add_i32 s56, s47, s35
	global_load_lds_dwordx4 v134, s[28:29]
	s_mov_b32 m0, s56
	s_nop 0
	global_load_lds_dwordx4 v130, s[54:55]
	s_add_i32 m0, s56, 0x2000
	s_nop 0
	global_load_lds_dwordx4 v134, s[54:55]
	s_mov_b32 m0, s36
	s_nop 0
	global_load_lds_dwordx4 v128, s[30:31]
	s_mov_b32 m0, s37
	s_nop 0
	global_load_lds_dwordx4 v132, s[30:31]
	s_add_u32 s86, s30, s4
	s_addc_u32 s87, s31, s5
	s_add_u32 s84, s28, s4
	s_addc_u32 s85, s29, s5
	s_waitcnt vmcnt(8)
	s_waitcnt lgkmcnt(0)
	s_barrier
	s_setprio 1
	s_waitcnt lgkmcnt(0)
	v_mfma_f32_16x16x32_bf16 v[60:63], v[176:179], v[208:211], 0
	v_mfma_f32_16x16x32_bf16 v[56:59], v[184:187], v[208:211], 0
	v_mfma_f32_16x16x32_bf16 v[44:47], v[176:179], v[216:219], 0
	v_mfma_f32_16x16x32_bf16 v[40:43], v[184:187], v[216:219], 0
	v_mfma_f32_16x16x32_bf16 v[28:31], v[176:179], v[224:227], 0
	v_mfma_f32_16x16x32_bf16 v[24:27], v[184:187], v[224:227], 0
	v_mfma_f32_16x16x32_bf16 v[12:15], v[176:179], v[234:237], 0
	v_mfma_f32_16x16x32_bf16 v[8:11], v[184:187], v[234:237], 0
	v_mfma_f32_16x16x32_bf16 v[60:63], v[180:183], v[212:215], v[60:63]
	v_mfma_f32_16x16x32_bf16 v[56:59], v[188:191], v[212:215], v[56:59]
	v_mfma_f32_16x16x32_bf16 v[44:47], v[180:183], v[220:223], v[44:47]
	v_mfma_f32_16x16x32_bf16 v[40:43], v[188:191], v[220:223], v[40:43]
	v_mfma_f32_16x16x32_bf16 v[28:31], v[180:183], v[230:233], v[28:31]
	v_mfma_f32_16x16x32_bf16 v[24:27], v[188:191], v[230:233], v[24:27]
	v_mfma_f32_16x16x32_bf16 v[12:15], v[180:183], v[238:241], v[12:15]
	v_mfma_f32_16x16x32_bf16 v[8:11], v[188:191], v[238:241], v[8:11]
	s_setprio 0
	s_setprio 1
	v_mfma_f32_16x16x32_bf16 v[52:55], v[192:195], v[208:211], 0
	v_mfma_f32_16x16x32_bf16 v[48:51], v[200:203], v[208:211], 0
	v_mfma_f32_16x16x32_bf16 v[36:39], v[192:195], v[216:219], 0
	v_mfma_f32_16x16x32_bf16 v[32:35], v[200:203], v[216:219], 0
	v_mfma_f32_16x16x32_bf16 v[20:23], v[192:195], v[224:227], 0
	v_mfma_f32_16x16x32_bf16 v[16:19], v[200:203], v[224:227], 0
	v_mfma_f32_16x16x32_bf16 v[4:7], v[192:195], v[234:237], 0
	v_mfma_f32_16x16x32_bf16 v[0:3], v[200:203], v[234:237], 0
	v_mfma_f32_16x16x32_bf16 v[52:55], v[196:199], v[212:215], v[52:55]
	v_mfma_f32_16x16x32_bf16 v[48:51], v[204:207], v[212:215], v[48:51]
	v_mfma_f32_16x16x32_bf16 v[36:39], v[196:199], v[220:223], v[36:39]
	v_mfma_f32_16x16x32_bf16 v[32:35], v[204:207], v[220:223], v[32:35]
	v_mfma_f32_16x16x32_bf16 v[20:23], v[196:199], v[230:233], v[20:23]
	v_mfma_f32_16x16x32_bf16 v[16:19], v[204:207], v[230:233], v[16:19]
	v_mfma_f32_16x16x32_bf16 v[4:7], v[196:199], v[238:241], v[4:7]
	v_mfma_f32_16x16x32_bf16 v[0:3], v[204:207], v[238:241], v[0:3]
	s_setprio 0
	s_barrier
	s_add_i32 s54, 0, 0x18000
	s_add_i32 s55, 0, 0x1c000
	v_add_u32_e32 v188, s54, v165
	v_add_u32_e32 v204, s55, v165
	ds_read_b128 v[176:179], v188
	ds_read_b128 v[180:183], v188 offset:1024
	ds_read_b128 v[184:187], v188 offset:2048
	ds_read_b128 v[188:191], v188 offset:3072
	ds_read_b128 v[192:195], v204
	ds_read_b128 v[196:199], v204 offset:1024
	ds_read_b128 v[200:203], v204 offset:2048
	ds_read_b128 v[204:207], v204 offset:3072
	s_add_u32 s30, s30, 0x40000
	s_addc_u32 s31, s31, 0
	s_mov_b32 m0, s41
	ds_read_b128 v[208:211], v167 offset:32768
	ds_read_b128 v[212:215], v167 offset:33792
	ds_read_b128 v[216:219], v167 offset:34816
	ds_read_b128 v[220:223], v167 offset:35840
	ds_read_b128 v[224:227], v167 offset:36864
	ds_read_b128 v[230:233], v167 offset:37888
	ds_read_b128 v[234:237], v167 offset:38912
	ds_read_b128 v[238:241], v167 offset:39936
	global_load_lds_dwordx4 v128, s[30:31]
	s_mov_b32 m0, s42
	s_nop 0
	global_load_lds_dwordx4 v132, s[30:31]
	s_waitcnt vmcnt(8)
	s_waitcnt lgkmcnt(0)
	s_barrier
	s_setprio 1
	s_waitcnt lgkmcnt(0)
	v_mfma_f32_16x16x32_bf16 v[124:127], v[176:179], v[208:211], v[124:127]
	v_mfma_f32_16x16x32_bf16 v[120:123], v[184:187], v[208:211], v[120:123]
	v_mfma_f32_16x16x32_bf16 v[108:111], v[176:179], v[216:219], v[108:111]
	v_mfma_f32_16x16x32_bf16 v[104:107], v[184:187], v[216:219], v[104:107]
	v_mfma_f32_16x16x32_bf16 v[92:95], v[176:179], v[224:227], v[92:95]
	v_mfma_f32_16x16x32_bf16 v[88:91], v[184:187], v[224:227], v[88:91]
	v_mfma_f32_16x16x32_bf16 v[76:79], v[176:179], v[234:237], v[76:79]
	v_mfma_f32_16x16x32_bf16 v[72:75], v[184:187], v[234:237], v[72:75]
	v_mfma_f32_16x16x32_bf16 v[124:127], v[180:183], v[212:215], v[124:127]
	v_mfma_f32_16x16x32_bf16 v[120:123], v[188:191], v[212:215], v[120:123]
	v_mfma_f32_16x16x32_bf16 v[108:111], v[180:183], v[220:223], v[108:111]
	v_mfma_f32_16x16x32_bf16 v[104:107], v[188:191], v[220:223], v[104:107]
	v_mfma_f32_16x16x32_bf16 v[92:95], v[180:183], v[230:233], v[92:95]
	v_mfma_f32_16x16x32_bf16 v[88:91], v[188:191], v[230:233], v[88:91]
	v_mfma_f32_16x16x32_bf16 v[76:79], v[180:183], v[238:241], v[76:79]
	v_mfma_f32_16x16x32_bf16 v[72:75], v[188:191], v[238:241], v[72:75]
	s_setprio 0
	s_setprio 1
	v_mfma_f32_16x16x32_bf16 v[116:119], v[192:195], v[208:211], v[116:119]
	v_mfma_f32_16x16x32_bf16 v[112:115], v[200:203], v[208:211], v[112:115]
	v_mfma_f32_16x16x32_bf16 v[100:103], v[192:195], v[216:219], v[100:103]
	v_mfma_f32_16x16x32_bf16 v[96:99], v[200:203], v[216:219], v[96:99]
	v_mfma_f32_16x16x32_bf16 v[84:87], v[192:195], v[224:227], v[84:87]
	v_mfma_f32_16x16x32_bf16 v[80:83], v[200:203], v[224:227], v[80:83]
	v_mfma_f32_16x16x32_bf16 v[68:71], v[192:195], v[234:237], v[68:71]
	v_mfma_f32_16x16x32_bf16 v[64:67], v[200:203], v[234:237], v[64:67]
	v_mfma_f32_16x16x32_bf16 v[116:119], v[196:199], v[212:215], v[116:119]
	v_mfma_f32_16x16x32_bf16 v[112:115], v[204:207], v[212:215], v[112:115]
	v_mfma_f32_16x16x32_bf16 v[100:103], v[196:199], v[220:223], v[100:103]
	v_mfma_f32_16x16x32_bf16 v[96:99], v[204:207], v[220:223], v[96:99]
	v_mfma_f32_16x16x32_bf16 v[84:87], v[196:199], v[230:233], v[84:87]
	v_mfma_f32_16x16x32_bf16 v[80:83], v[204:207], v[230:233], v[80:83]
	v_mfma_f32_16x16x32_bf16 v[68:71], v[196:199], v[238:241], v[68:71]
	v_mfma_f32_16x16x32_bf16 v[64:67], v[204:207], v[238:241], v[64:67]
	s_setprio 0
	s_barrier
	s_add_i32 s30, s54, s35
	s_mov_b32 m0, s30
	ds_read_b128 v[208:211], v167 offset:49152
	ds_read_b128 v[212:215], v167 offset:50176
	ds_read_b128 v[216:219], v167 offset:51200
	ds_read_b128 v[220:223], v167 offset:52224
	ds_read_b128 v[224:227], v167 offset:53248
	ds_read_b128 v[230:233], v167 offset:54272
	ds_read_b128 v[234:237], v167 offset:55296
	ds_read_b128 v[238:241], v167 offset:56320
	global_load_lds_dwordx4 v130, s[84:85]
	s_add_i32 m0, s30, 0x2000
	s_add_u32 s28, s28, 0x40080
	s_addc_u32 s29, s29, 0
	s_add_i32 s30, s55, s35
	global_load_lds_dwordx4 v134, s[84:85]
	s_mov_b32 m0, s30
	s_nop 0
	global_load_lds_dwordx4 v130, s[28:29]
	s_add_i32 m0, s30, 0x2000
	s_nop 0
	global_load_lds_dwordx4 v134, s[28:29]
	s_mov_b32 m0, s44
	s_nop 0
	global_load_lds_dwordx4 v128, s[86:87]
	s_mov_b32 m0, s45
	s_nop 0
	global_load_lds_dwordx4 v132, s[86:87]
	s_waitcnt vmcnt(8)
	s_waitcnt lgkmcnt(0)
	s_barrier
	s_setprio 1
	s_waitcnt lgkmcnt(0)
	v_mfma_f32_16x16x32_bf16 v[60:63], v[176:179], v[208:211], v[60:63]
	v_mfma_f32_16x16x32_bf16 v[56:59], v[184:187], v[208:211], v[56:59]
	v_mfma_f32_16x16x32_bf16 v[44:47], v[176:179], v[216:219], v[44:47]
	v_mfma_f32_16x16x32_bf16 v[40:43], v[184:187], v[216:219], v[40:43]
	v_mfma_f32_16x16x32_bf16 v[28:31], v[176:179], v[224:227], v[28:31]
	v_mfma_f32_16x16x32_bf16 v[24:27], v[184:187], v[224:227], v[24:27]
	v_mfma_f32_16x16x32_bf16 v[12:15], v[176:179], v[234:237], v[12:15]
	v_mfma_f32_16x16x32_bf16 v[8:11], v[184:187], v[234:237], v[8:11]
	v_mfma_f32_16x16x32_bf16 v[60:63], v[180:183], v[212:215], v[60:63]
	v_mfma_f32_16x16x32_bf16 v[56:59], v[188:191], v[212:215], v[56:59]
	v_mfma_f32_16x16x32_bf16 v[44:47], v[180:183], v[220:223], v[44:47]
	v_mfma_f32_16x16x32_bf16 v[40:43], v[188:191], v[220:223], v[40:43]
	v_mfma_f32_16x16x32_bf16 v[28:31], v[180:183], v[230:233], v[28:31]
	v_mfma_f32_16x16x32_bf16 v[24:27], v[188:191], v[230:233], v[24:27]
	v_mfma_f32_16x16x32_bf16 v[12:15], v[180:183], v[238:241], v[12:15]
	v_mfma_f32_16x16x32_bf16 v[8:11], v[188:191], v[238:241], v[8:11]
	s_setprio 0
	s_setprio 1
	v_mfma_f32_16x16x32_bf16 v[52:55], v[192:195], v[208:211], v[52:55]
	v_mfma_f32_16x16x32_bf16 v[48:51], v[200:203], v[208:211], v[48:51]
	v_mfma_f32_16x16x32_bf16 v[36:39], v[192:195], v[216:219], v[36:39]
	v_mfma_f32_16x16x32_bf16 v[32:35], v[200:203], v[216:219], v[32:35]
	v_mfma_f32_16x16x32_bf16 v[20:23], v[192:195], v[224:227], v[20:23]
	v_mfma_f32_16x16x32_bf16 v[16:19], v[200:203], v[224:227], v[16:19]
	v_mfma_f32_16x16x32_bf16 v[4:7], v[192:195], v[234:237], v[4:7]
	v_mfma_f32_16x16x32_bf16 v[0:3], v[200:203], v[234:237], v[0:3]
	v_mfma_f32_16x16x32_bf16 v[52:55], v[196:199], v[212:215], v[52:55]
	v_mfma_f32_16x16x32_bf16 v[48:51], v[204:207], v[212:215], v[48:51]
	v_mfma_f32_16x16x32_bf16 v[36:39], v[196:199], v[220:223], v[36:39]
	v_mfma_f32_16x16x32_bf16 v[32:35], v[204:207], v[220:223], v[32:35]
	v_mfma_f32_16x16x32_bf16 v[20:23], v[196:199], v[230:233], v[20:23]
	v_mfma_f32_16x16x32_bf16 v[16:19], v[204:207], v[230:233], v[16:19]
	v_mfma_f32_16x16x32_bf16 v[4:7], v[196:199], v[238:241], v[4:7]
	v_mfma_f32_16x16x32_bf16 v[0:3], v[204:207], v[238:241], v[0:3]
	s_setprio 0
	s_barrier
	s_add_i32 s53, s53, 2
	s_add_u32 s26, s26, 0x100
	s_addc_u32 s27, s27, 0
	s_add_u32 s51, s51, 0x100
	s_addc_u32 s52, s52, 0
	s_branch .LBB0_499
.LBB0_498:
	v_add_u32_e32 v188, s46, v165
	v_add_u32_e32 v204, s47, v165
	ds_read_b128 v[176:179], v188
	ds_read_b128 v[180:183], v188 offset:1024
	ds_read_b128 v[184:187], v188 offset:2048
	ds_read_b128 v[188:191], v188 offset:3072
	ds_read_b128 v[192:195], v204
	ds_read_b128 v[196:199], v204 offset:1024
	ds_read_b128 v[200:203], v204 offset:2048
	ds_read_b128 v[204:207], v204 offset:3072
	s_add_u32 s30, s26, 0xfffc0080
	s_addc_u32 s31, s27, -1
	s_and_b64 s[28:29], s[28:29], exec
	s_cselect_b32 s31, s11, s31
	s_cselect_b32 s30, s49, s30
	s_cselect_b32 s29, s9, s52
	s_cselect_b32 s28, s50, s51
	s_add_i32 m0, s36, 0xc000
	ds_read_b128 v[208:211], v167
	ds_read_b128 v[212:215], v167 offset:1024
	ds_read_b128 v[216:219], v167 offset:2048
	ds_read_b128 v[220:223], v167 offset:3072
	ds_read_b128 v[224:227], v167 offset:4096
	ds_read_b128 v[230:233], v167 offset:5120
	ds_read_b128 v[234:237], v167 offset:6144
	ds_read_b128 v[238:241], v167 offset:7168
	global_load_lds_dwordx4 v136, s[26:27]
	s_add_i32 m0, s36, 0xe000
	s_nop 0
	global_load_lds_dwordx4 v138, s[26:27]
	s_waitcnt vmcnt(8)
	s_waitcnt lgkmcnt(0)
	s_barrier
	s_setprio 1
	s_waitcnt lgkmcnt(0)
	v_mfma_f32_16x16x32_bf16 v[124:127], v[176:179], v[208:211], v[124:127]
	v_mfma_f32_16x16x32_bf16 v[120:123], v[184:187], v[208:211], v[120:123]
	v_mfma_f32_16x16x32_bf16 v[108:111], v[176:179], v[216:219], v[108:111]
	v_mfma_f32_16x16x32_bf16 v[104:107], v[184:187], v[216:219], v[104:107]
	v_mfma_f32_16x16x32_bf16 v[92:95], v[176:179], v[224:227], v[92:95]
	v_mfma_f32_16x16x32_bf16 v[88:91], v[184:187], v[224:227], v[88:91]
	v_mfma_f32_16x16x32_bf16 v[76:79], v[176:179], v[234:237], v[76:79]
	v_mfma_f32_16x16x32_bf16 v[72:75], v[184:187], v[234:237], v[72:75]
	v_mfma_f32_16x16x32_bf16 v[124:127], v[180:183], v[212:215], v[124:127]
	v_mfma_f32_16x16x32_bf16 v[120:123], v[188:191], v[212:215], v[120:123]
	v_mfma_f32_16x16x32_bf16 v[108:111], v[180:183], v[220:223], v[108:111]
	v_mfma_f32_16x16x32_bf16 v[104:107], v[188:191], v[220:223], v[104:107]
	v_mfma_f32_16x16x32_bf16 v[92:95], v[180:183], v[230:233], v[92:95]
	v_mfma_f32_16x16x32_bf16 v[88:91], v[188:191], v[230:233], v[88:91]
	v_mfma_f32_16x16x32_bf16 v[76:79], v[180:183], v[238:241], v[76:79]
	v_mfma_f32_16x16x32_bf16 v[72:75], v[188:191], v[238:241], v[72:75]
	s_setprio 0
	s_setprio 1
	v_mfma_f32_16x16x32_bf16 v[116:119], v[192:195], v[208:211], v[116:119]
	v_mfma_f32_16x16x32_bf16 v[112:115], v[200:203], v[208:211], v[112:115]
	v_mfma_f32_16x16x32_bf16 v[100:103], v[192:195], v[216:219], v[100:103]
	v_mfma_f32_16x16x32_bf16 v[96:99], v[200:203], v[216:219], v[96:99]
	v_mfma_f32_16x16x32_bf16 v[84:87], v[192:195], v[224:227], v[84:87]
	v_mfma_f32_16x16x32_bf16 v[80:83], v[200:203], v[224:227], v[80:83]
	v_mfma_f32_16x16x32_bf16 v[68:71], v[192:195], v[234:237], v[68:71]
	v_mfma_f32_16x16x32_bf16 v[64:67], v[200:203], v[234:237], v[64:67]
	v_mfma_f32_16x16x32_bf16 v[116:119], v[196:199], v[212:215], v[116:119]
	v_mfma_f32_16x16x32_bf16 v[112:115], v[204:207], v[212:215], v[112:115]
	v_mfma_f32_16x16x32_bf16 v[100:103], v[196:199], v[220:223], v[100:103]
	v_mfma_f32_16x16x32_bf16 v[96:99], v[204:207], v[220:223], v[96:99]
	v_mfma_f32_16x16x32_bf16 v[84:87], v[196:199], v[230:233], v[84:87]
	v_mfma_f32_16x16x32_bf16 v[80:83], v[204:207], v[230:233], v[80:83]
	v_mfma_f32_16x16x32_bf16 v[68:71], v[196:199], v[238:241], v[68:71]
	v_mfma_f32_16x16x32_bf16 v[64:67], v[204:207], v[238:241], v[64:67]
	s_setprio 0
	s_barrier
	s_add_i32 s54, s46, s35
	s_mov_b32 m0, s54
	ds_read_b128 v[208:211], v167 offset:16384
	ds_read_b128 v[212:215], v167 offset:17408
	ds_read_b128 v[216:219], v167 offset:18432
	ds_read_b128 v[220:223], v167 offset:19456
	ds_read_b128 v[224:227], v167 offset:20480
	ds_read_b128 v[230:233], v167 offset:21504
	ds_read_b128 v[234:237], v167 offset:22528
	ds_read_b128 v[238:241], v167 offset:23552
	global_load_lds_dwordx4 v130, s[28:29]
	s_add_i32 m0, s54, 0x2000
	s_add_u32 s54, s28, 0x40000
	s_addc_u32 s55, s29, 0
	s_add_i32 s56, s47, s35
	global_load_lds_dwordx4 v134, s[28:29]
	s_mov_b32 m0, s56
	s_nop 0
	global_load_lds_dwordx4 v130, s[54:55]
	s_add_i32 m0, s56, 0x2000
	s_nop 0
	global_load_lds_dwordx4 v134, s[54:55]
	s_mov_b32 m0, s36
	s_nop 0
	global_load_lds_dwordx4 v128, s[30:31]
	s_mov_b32 m0, s37
	s_nop 0
	global_load_lds_dwordx4 v132, s[30:31]
	s_add_u32 s86, s30, s4
	s_addc_u32 s87, s31, s5
	s_add_u32 s84, s28, s4
	s_addc_u32 s85, s29, s5
	s_waitcnt vmcnt(8)
	s_waitcnt lgkmcnt(0)
	s_barrier
	s_setprio 1
	s_waitcnt lgkmcnt(0)
	v_mfma_f32_16x16x32_bf16 v[60:63], v[176:179], v[208:211], v[60:63]
	v_mfma_f32_16x16x32_bf16 v[56:59], v[184:187], v[208:211], v[56:59]
	v_mfma_f32_16x16x32_bf16 v[44:47], v[176:179], v[216:219], v[44:47]
	v_mfma_f32_16x16x32_bf16 v[40:43], v[184:187], v[216:219], v[40:43]
	v_mfma_f32_16x16x32_bf16 v[28:31], v[176:179], v[224:227], v[28:31]
	v_mfma_f32_16x16x32_bf16 v[24:27], v[184:187], v[224:227], v[24:27]
	v_mfma_f32_16x16x32_bf16 v[12:15], v[176:179], v[234:237], v[12:15]
	v_mfma_f32_16x16x32_bf16 v[8:11], v[184:187], v[234:237], v[8:11]
	v_mfma_f32_16x16x32_bf16 v[60:63], v[180:183], v[212:215], v[60:63]
	v_mfma_f32_16x16x32_bf16 v[56:59], v[188:191], v[212:215], v[56:59]
	v_mfma_f32_16x16x32_bf16 v[44:47], v[180:183], v[220:223], v[44:47]
	v_mfma_f32_16x16x32_bf16 v[40:43], v[188:191], v[220:223], v[40:43]
	v_mfma_f32_16x16x32_bf16 v[28:31], v[180:183], v[230:233], v[28:31]
	v_mfma_f32_16x16x32_bf16 v[24:27], v[188:191], v[230:233], v[24:27]
	v_mfma_f32_16x16x32_bf16 v[12:15], v[180:183], v[238:241], v[12:15]
	v_mfma_f32_16x16x32_bf16 v[8:11], v[188:191], v[238:241], v[8:11]
	s_setprio 0
	s_setprio 1
	v_mfma_f32_16x16x32_bf16 v[52:55], v[192:195], v[208:211], v[52:55]
	v_mfma_f32_16x16x32_bf16 v[48:51], v[200:203], v[208:211], v[48:51]
	v_mfma_f32_16x16x32_bf16 v[36:39], v[192:195], v[216:219], v[36:39]
	v_mfma_f32_16x16x32_bf16 v[32:35], v[200:203], v[216:219], v[32:35]
	v_mfma_f32_16x16x32_bf16 v[20:23], v[192:195], v[224:227], v[20:23]
	v_mfma_f32_16x16x32_bf16 v[16:19], v[200:203], v[224:227], v[16:19]
	v_mfma_f32_16x16x32_bf16 v[4:7], v[192:195], v[234:237], v[4:7]
	v_mfma_f32_16x16x32_bf16 v[0:3], v[200:203], v[234:237], v[0:3]
	v_mfma_f32_16x16x32_bf16 v[52:55], v[196:199], v[212:215], v[52:55]
	v_mfma_f32_16x16x32_bf16 v[48:51], v[204:207], v[212:215], v[48:51]
	v_mfma_f32_16x16x32_bf16 v[36:39], v[196:199], v[220:223], v[36:39]
	v_mfma_f32_16x16x32_bf16 v[32:35], v[204:207], v[220:223], v[32:35]
	v_mfma_f32_16x16x32_bf16 v[20:23], v[196:199], v[230:233], v[20:23]
	v_mfma_f32_16x16x32_bf16 v[16:19], v[204:207], v[230:233], v[16:19]
	v_mfma_f32_16x16x32_bf16 v[4:7], v[196:199], v[238:241], v[4:7]
	v_mfma_f32_16x16x32_bf16 v[0:3], v[204:207], v[238:241], v[0:3]
	s_setprio 0
	s_barrier
	s_add_i32 s54, 0, 0x18000
	s_add_i32 s55, 0, 0x1c000
	v_add_u32_e32 v188, s54, v165
	v_add_u32_e32 v204, s55, v165
	ds_read_b128 v[176:179], v188
	ds_read_b128 v[180:183], v188 offset:1024
	ds_read_b128 v[184:187], v188 offset:2048
	ds_read_b128 v[188:191], v188 offset:3072
	ds_read_b128 v[192:195], v204
	ds_read_b128 v[196:199], v204 offset:1024
	ds_read_b128 v[200:203], v204 offset:2048
	ds_read_b128 v[204:207], v204 offset:3072
	s_add_u32 s30, s30, 0x40000
	s_addc_u32 s31, s31, 0
	s_mov_b32 m0, s41
	ds_read_b128 v[208:211], v167 offset:32768
	ds_read_b128 v[212:215], v167 offset:33792
	ds_read_b128 v[216:219], v167 offset:34816
	ds_read_b128 v[220:223], v167 offset:35840
	ds_read_b128 v[224:227], v167 offset:36864
	ds_read_b128 v[230:233], v167 offset:37888
	ds_read_b128 v[234:237], v167 offset:38912
	ds_read_b128 v[238:241], v167 offset:39936
	global_load_lds_dwordx4 v128, s[30:31]
	s_mov_b32 m0, s42
	s_nop 0
	global_load_lds_dwordx4 v132, s[30:31]
	s_waitcnt vmcnt(8)
	s_waitcnt lgkmcnt(0)
	s_barrier
	s_setprio 1
	s_waitcnt lgkmcnt(0)
	v_mfma_f32_16x16x32_bf16 v[124:127], v[176:179], v[208:211], v[124:127]
	v_mfma_f32_16x16x32_bf16 v[120:123], v[184:187], v[208:211], v[120:123]
	v_mfma_f32_16x16x32_bf16 v[108:111], v[176:179], v[216:219], v[108:111]
	v_mfma_f32_16x16x32_bf16 v[104:107], v[184:187], v[216:219], v[104:107]
	v_mfma_f32_16x16x32_bf16 v[92:95], v[176:179], v[224:227], v[92:95]
	v_mfma_f32_16x16x32_bf16 v[88:91], v[184:187], v[224:227], v[88:91]
	v_mfma_f32_16x16x32_bf16 v[76:79], v[176:179], v[234:237], v[76:79]
	v_mfma_f32_16x16x32_bf16 v[72:75], v[184:187], v[234:237], v[72:75]
	v_mfma_f32_16x16x32_bf16 v[124:127], v[180:183], v[212:215], v[124:127]
	v_mfma_f32_16x16x32_bf16 v[120:123], v[188:191], v[212:215], v[120:123]
	v_mfma_f32_16x16x32_bf16 v[108:111], v[180:183], v[220:223], v[108:111]
	v_mfma_f32_16x16x32_bf16 v[104:107], v[188:191], v[220:223], v[104:107]
	v_mfma_f32_16x16x32_bf16 v[92:95], v[180:183], v[230:233], v[92:95]
	v_mfma_f32_16x16x32_bf16 v[88:91], v[188:191], v[230:233], v[88:91]
	v_mfma_f32_16x16x32_bf16 v[76:79], v[180:183], v[238:241], v[76:79]
	v_mfma_f32_16x16x32_bf16 v[72:75], v[188:191], v[238:241], v[72:75]
	s_setprio 0
	s_setprio 1
	v_mfma_f32_16x16x32_bf16 v[116:119], v[192:195], v[208:211], v[116:119]
	v_mfma_f32_16x16x32_bf16 v[112:115], v[200:203], v[208:211], v[112:115]
	v_mfma_f32_16x16x32_bf16 v[100:103], v[192:195], v[216:219], v[100:103]
	v_mfma_f32_16x16x32_bf16 v[96:99], v[200:203], v[216:219], v[96:99]
	v_mfma_f32_16x16x32_bf16 v[84:87], v[192:195], v[224:227], v[84:87]
	v_mfma_f32_16x16x32_bf16 v[80:83], v[200:203], v[224:227], v[80:83]
	v_mfma_f32_16x16x32_bf16 v[68:71], v[192:195], v[234:237], v[68:71]
	v_mfma_f32_16x16x32_bf16 v[64:67], v[200:203], v[234:237], v[64:67]
	v_mfma_f32_16x16x32_bf16 v[116:119], v[196:199], v[212:215], v[116:119]
	v_mfma_f32_16x16x32_bf16 v[112:115], v[204:207], v[212:215], v[112:115]
	v_mfma_f32_16x16x32_bf16 v[100:103], v[196:199], v[220:223], v[100:103]
	v_mfma_f32_16x16x32_bf16 v[96:99], v[204:207], v[220:223], v[96:99]
	v_mfma_f32_16x16x32_bf16 v[84:87], v[196:199], v[230:233], v[84:87]
	v_mfma_f32_16x16x32_bf16 v[80:83], v[204:207], v[230:233], v[80:83]
	v_mfma_f32_16x16x32_bf16 v[68:71], v[196:199], v[238:241], v[68:71]
	v_mfma_f32_16x16x32_bf16 v[64:67], v[204:207], v[238:241], v[64:67]
	s_setprio 0
	s_barrier
	s_add_i32 s30, s54, s35
	s_mov_b32 m0, s30
	ds_read_b128 v[208:211], v167 offset:49152
	ds_read_b128 v[212:215], v167 offset:50176
	ds_read_b128 v[216:219], v167 offset:51200
	ds_read_b128 v[220:223], v167 offset:52224
	ds_read_b128 v[224:227], v167 offset:53248
	ds_read_b128 v[230:233], v167 offset:54272
	ds_read_b128 v[234:237], v167 offset:55296
	ds_read_b128 v[238:241], v167 offset:56320
	global_load_lds_dwordx4 v130, s[84:85]
	s_add_i32 m0, s30, 0x2000
	s_add_u32 s28, s28, 0x40080
	s_addc_u32 s29, s29, 0
	s_add_i32 s30, s55, s35
	global_load_lds_dwordx4 v134, s[84:85]
	s_mov_b32 m0, s30
	s_nop 0
	global_load_lds_dwordx4 v130, s[28:29]
	s_add_i32 m0, s30, 0x2000
	s_nop 0
	global_load_lds_dwordx4 v134, s[28:29]
	s_mov_b32 m0, s44
	s_nop 0
	global_load_lds_dwordx4 v128, s[86:87]
	s_mov_b32 m0, s45
	s_nop 0
	global_load_lds_dwordx4 v132, s[86:87]
	s_waitcnt vmcnt(8)
	s_waitcnt lgkmcnt(0)
	s_barrier
	s_setprio 1
	s_waitcnt lgkmcnt(0)
	v_mfma_f32_16x16x32_bf16 v[60:63], v[176:179], v[208:211], v[60:63]
	v_mfma_f32_16x16x32_bf16 v[56:59], v[184:187], v[208:211], v[56:59]
	v_mfma_f32_16x16x32_bf16 v[44:47], v[176:179], v[216:219], v[44:47]
	v_mfma_f32_16x16x32_bf16 v[40:43], v[184:187], v[216:219], v[40:43]
	v_mfma_f32_16x16x32_bf16 v[28:31], v[176:179], v[224:227], v[28:31]
	v_mfma_f32_16x16x32_bf16 v[24:27], v[184:187], v[224:227], v[24:27]
	v_mfma_f32_16x16x32_bf16 v[12:15], v[176:179], v[234:237], v[12:15]
	v_mfma_f32_16x16x32_bf16 v[8:11], v[184:187], v[234:237], v[8:11]
	v_mfma_f32_16x16x32_bf16 v[60:63], v[180:183], v[212:215], v[60:63]
	v_mfma_f32_16x16x32_bf16 v[56:59], v[188:191], v[212:215], v[56:59]
	v_mfma_f32_16x16x32_bf16 v[44:47], v[180:183], v[220:223], v[44:47]
	v_mfma_f32_16x16x32_bf16 v[40:43], v[188:191], v[220:223], v[40:43]
	v_mfma_f32_16x16x32_bf16 v[28:31], v[180:183], v[230:233], v[28:31]
	v_mfma_f32_16x16x32_bf16 v[24:27], v[188:191], v[230:233], v[24:27]
	v_mfma_f32_16x16x32_bf16 v[12:15], v[180:183], v[238:241], v[12:15]
	v_mfma_f32_16x16x32_bf16 v[8:11], v[188:191], v[238:241], v[8:11]
	s_setprio 0
	s_setprio 1
	v_mfma_f32_16x16x32_bf16 v[52:55], v[192:195], v[208:211], v[52:55]
	v_mfma_f32_16x16x32_bf16 v[48:51], v[200:203], v[208:211], v[48:51]
	v_mfma_f32_16x16x32_bf16 v[36:39], v[192:195], v[216:219], v[36:39]
	v_mfma_f32_16x16x32_bf16 v[32:35], v[200:203], v[216:219], v[32:35]
	v_mfma_f32_16x16x32_bf16 v[20:23], v[192:195], v[224:227], v[20:23]
	v_mfma_f32_16x16x32_bf16 v[16:19], v[200:203], v[224:227], v[16:19]
	v_mfma_f32_16x16x32_bf16 v[4:7], v[192:195], v[234:237], v[4:7]
	v_mfma_f32_16x16x32_bf16 v[0:3], v[200:203], v[234:237], v[0:3]
	v_mfma_f32_16x16x32_bf16 v[52:55], v[196:199], v[212:215], v[52:55]
	v_mfma_f32_16x16x32_bf16 v[48:51], v[204:207], v[212:215], v[48:51]
	v_mfma_f32_16x16x32_bf16 v[36:39], v[196:199], v[220:223], v[36:39]
	v_mfma_f32_16x16x32_bf16 v[32:35], v[204:207], v[220:223], v[32:35]
	v_mfma_f32_16x16x32_bf16 v[20:23], v[196:199], v[230:233], v[20:23]
	v_mfma_f32_16x16x32_bf16 v[16:19], v[204:207], v[230:233], v[16:19]
	v_mfma_f32_16x16x32_bf16 v[4:7], v[196:199], v[238:241], v[4:7]
	v_mfma_f32_16x16x32_bf16 v[0:3], v[204:207], v[238:241], v[0:3]
	s_setprio 0
	s_barrier
	s_add_i32 s53, s53, 2
	s_add_u32 s26, s26, 0x100
	s_addc_u32 s27, s27, 0
	s_add_u32 s51, s51, 0x100
	s_addc_u32 s52, s52, 0
	s_cmp_gt_u32 s53, 13
	s_cbranch_scc1 .LBB0_501

.LBB0_599:
	s_add_u32 s20, s50, s18
	s_addc_u32 s21, s51, s19
	s_add_u32 s20, s20, 0x1d80100
	s_addc_u32 s21, s21, 0
	s_add_u32 s55, s52, s18
	s_addc_u32 s56, s53, s19
	s_add_i32 s57, 0, 0x10000
	s_cmpk_eq_i32 s18, 0x1f00
	s_cselect_b32 s23, s11, s21
	s_cselect_b32 s22, s10, s20
	s_cselect_b32 s21, s1, s56
	s_cselect_b32 s20, s0, s55
	s_add_i32 s55, 0, 0x14000
	v_add_u32_e32 v152, s57, v138
	v_add_u32_e32 v168, s55, v138
	ds_read_b128 v[140:143], v152
	ds_read_b128 v[144:147], v152 offset:1024
	ds_read_b128 v[148:151], v152 offset:2048
	ds_read_b128 v[152:155], v152 offset:3072
	ds_read_b128 v[156:159], v168
	ds_read_b128 v[160:163], v168 offset:1024
	ds_read_b128 v[164:167], v168 offset:2048
	ds_read_b128 v[168:171], v168 offset:3072
	v_lshl_add_u64 v[180:181], v[134:135], 0, s[18:19]
	s_add_i32 m0, s43, 0xc000
	ds_read_b128 v[172:175], v139
	ds_read_b128 v[176:179], v139 offset:1024
	ds_read_b128 v[184:187], v139 offset:2048
	ds_read_b128 v[188:191], v139 offset:3072
	ds_read_b128 v[192:195], v139 offset:4096
	ds_read_b128 v[196:199], v139 offset:5120
	ds_read_b128 v[200:203], v139 offset:6144
	ds_read_b128 v[204:207], v139 offset:7168
	global_load_lds_dwordx4 v[180:181], off
	v_lshl_add_u64 v[180:181], v[136:137], 0, s[18:19]
	s_add_i32 m0, s43, 0xe000
	s_nop 0
	global_load_lds_dwordx4 v[180:181], off
	s_waitcnt vmcnt(8)
	s_waitcnt lgkmcnt(0)
	s_barrier
	s_setprio 1
	s_waitcnt lgkmcnt(0)
	v_mfma_f32_16x16x32_bf16 v[124:127], v[140:143], v[172:175], v[124:127]
	v_mfma_f32_16x16x32_bf16 v[120:123], v[148:151], v[172:175], v[120:123]
	v_mfma_f32_16x16x32_bf16 v[116:119], v[140:143], v[184:187], v[116:119]
	v_mfma_f32_16x16x32_bf16 v[112:115], v[148:151], v[184:187], v[112:115]
	v_mfma_f32_16x16x32_bf16 v[92:95], v[140:143], v[192:195], v[92:95]
	v_mfma_f32_16x16x32_bf16 v[88:91], v[148:151], v[192:195], v[88:91]
	v_mfma_f32_16x16x32_bf16 v[80:83], v[140:143], v[200:203], v[80:83]
	v_mfma_f32_16x16x32_bf16 v[72:75], v[148:151], v[200:203], v[72:75]
	v_mfma_f32_16x16x32_bf16 v[124:127], v[144:147], v[176:179], v[124:127]
	v_mfma_f32_16x16x32_bf16 v[120:123], v[152:155], v[176:179], v[120:123]
	v_mfma_f32_16x16x32_bf16 v[116:119], v[144:147], v[188:191], v[116:119]
	v_mfma_f32_16x16x32_bf16 v[112:115], v[152:155], v[188:191], v[112:115]
	v_mfma_f32_16x16x32_bf16 v[92:95], v[144:147], v[196:199], v[92:95]
	v_mfma_f32_16x16x32_bf16 v[88:91], v[152:155], v[196:199], v[88:91]
	v_mfma_f32_16x16x32_bf16 v[80:83], v[144:147], v[204:207], v[80:83]
	v_mfma_f32_16x16x32_bf16 v[72:75], v[152:155], v[204:207], v[72:75]
	s_setprio 0
	s_setprio 1
	v_mfma_f32_16x16x32_bf16 v[108:111], v[156:159], v[172:175], v[108:111]
	v_mfma_f32_16x16x32_bf16 v[104:107], v[164:167], v[172:175], v[104:107]
	v_mfma_f32_16x16x32_bf16 v[100:103], v[156:159], v[184:187], v[100:103]
	v_mfma_f32_16x16x32_bf16 v[96:99], v[164:167], v[184:187], v[96:99]
	v_mfma_f32_16x16x32_bf16 v[84:87], v[156:159], v[192:195], v[84:87]
	v_mfma_f32_16x16x32_bf16 v[76:79], v[164:167], v[192:195], v[76:79]
	v_mfma_f32_16x16x32_bf16 v[68:71], v[156:159], v[200:203], v[68:71]
	v_mfma_f32_16x16x32_bf16 v[64:67], v[164:167], v[200:203], v[64:67]
	v_mfma_f32_16x16x32_bf16 v[108:111], v[160:163], v[176:179], v[108:111]
	v_mfma_f32_16x16x32_bf16 v[104:107], v[168:171], v[176:179], v[104:107]
	v_mfma_f32_16x16x32_bf16 v[100:103], v[160:163], v[188:191], v[100:103]
	v_mfma_f32_16x16x32_bf16 v[96:99], v[168:171], v[188:191], v[96:99]
	v_mfma_f32_16x16x32_bf16 v[84:87], v[160:163], v[196:199], v[84:87]
	v_mfma_f32_16x16x32_bf16 v[76:79], v[168:171], v[196:199], v[76:79]
	v_mfma_f32_16x16x32_bf16 v[68:71], v[160:163], v[204:207], v[68:71]
	v_mfma_f32_16x16x32_bf16 v[64:67], v[168:171], v[204:207], v[64:67]
	s_setprio 0
	s_barrier
	s_add_i32 s56, s57, s42
	s_mov_b32 m0, s56
	ds_read_b128 v[172:175], v139 offset:16384
	ds_read_b128 v[176:179], v139 offset:17408
	ds_read_b128 v[184:187], v139 offset:18432
	ds_read_b128 v[188:191], v139 offset:19456
	ds_read_b128 v[192:195], v139 offset:20480
	ds_read_b128 v[196:199], v139 offset:21504
	ds_read_b128 v[200:203], v139 offset:22528
	ds_read_b128 v[204:207], v139 offset:23552
	global_load_lds_dwordx4 v212, s[20:21]
	s_add_i32 m0, s56, 0x2000
	s_add_u32 s56, s20, 0x100000
	s_addc_u32 s57, s21, 0
	s_add_i32 s55, s55, s42
	global_load_lds_dwordx4 v128, s[20:21]
	s_mov_b32 m0, s55
	s_nop 0
	global_load_lds_dwordx4 v212, s[56:57]
	s_add_i32 m0, s55, 0x2000
	s_nop 0
	global_load_lds_dwordx4 v128, s[56:57]
	s_mov_b32 m0, s43
	s_nop 0
	global_load_lds_dwordx4 v132, s[22:23]
	s_mov_b32 m0, s44
	s_nop 0
	global_load_lds_dwordx4 v130, s[22:23]
	s_add_u32 s86, s22, s4
	s_addc_u32 s87, s23, s5
	s_add_u32 s84, s20, s4
	s_addc_u32 s85, s21, s5
	s_waitcnt vmcnt(8)
	s_waitcnt lgkmcnt(0)
	s_barrier
	s_setprio 1
	s_waitcnt lgkmcnt(0)
	v_mfma_f32_16x16x32_bf16 v[60:63], v[140:143], v[172:175], v[60:63]
	v_mfma_f32_16x16x32_bf16 v[56:59], v[148:151], v[172:175], v[56:59]
	v_mfma_f32_16x16x32_bf16 v[48:51], v[140:143], v[184:187], v[48:51]
	v_mfma_f32_16x16x32_bf16 v[40:43], v[148:151], v[184:187], v[40:43]
	v_mfma_f32_16x16x32_bf16 v[28:31], v[140:143], v[192:195], v[28:31]
	v_mfma_f32_16x16x32_bf16 v[24:27], v[148:151], v[192:195], v[24:27]
	v_mfma_f32_16x16x32_bf16 v[16:19], v[140:143], v[200:203], v[16:19]
	v_mfma_f32_16x16x32_bf16 v[8:11], v[148:151], v[200:203], v[8:11]
	v_mfma_f32_16x16x32_bf16 v[60:63], v[144:147], v[176:179], v[60:63]
	v_mfma_f32_16x16x32_bf16 v[56:59], v[152:155], v[176:179], v[56:59]
	v_mfma_f32_16x16x32_bf16 v[48:51], v[144:147], v[188:191], v[48:51]
	v_mfma_f32_16x16x32_bf16 v[40:43], v[152:155], v[188:191], v[40:43]
	v_mfma_f32_16x16x32_bf16 v[28:31], v[144:147], v[196:199], v[28:31]
	v_mfma_f32_16x16x32_bf16 v[24:27], v[152:155], v[196:199], v[24:27]
	v_mfma_f32_16x16x32_bf16 v[16:19], v[144:147], v[204:207], v[16:19]
	v_mfma_f32_16x16x32_bf16 v[8:11], v[152:155], v[204:207], v[8:11]
	s_setprio 0
	s_setprio 1
	v_mfma_f32_16x16x32_bf16 v[52:55], v[156:159], v[172:175], v[52:55]
	v_mfma_f32_16x16x32_bf16 v[44:47], v[164:167], v[172:175], v[44:47]
	v_mfma_f32_16x16x32_bf16 v[36:39], v[156:159], v[184:187], v[36:39]
	v_mfma_f32_16x16x32_bf16 v[32:35], v[164:167], v[184:187], v[32:35]
	v_mfma_f32_16x16x32_bf16 v[20:23], v[156:159], v[192:195], v[20:23]
	v_mfma_f32_16x16x32_bf16 v[12:15], v[164:167], v[192:195], v[12:15]
	v_mfma_f32_16x16x32_bf16 v[4:7], v[156:159], v[200:203], v[4:7]
	v_mfma_f32_16x16x32_bf16 v[0:3], v[164:167], v[200:203], v[0:3]
	v_mfma_f32_16x16x32_bf16 v[52:55], v[160:163], v[176:179], v[52:55]
	v_mfma_f32_16x16x32_bf16 v[44:47], v[168:171], v[176:179], v[44:47]
	v_mfma_f32_16x16x32_bf16 v[36:39], v[160:163], v[188:191], v[36:39]
	v_mfma_f32_16x16x32_bf16 v[32:35], v[168:171], v[188:191], v[32:35]
	v_mfma_f32_16x16x32_bf16 v[20:23], v[160:163], v[196:199], v[20:23]
	v_mfma_f32_16x16x32_bf16 v[12:15], v[168:171], v[196:199], v[12:15]
	v_mfma_f32_16x16x32_bf16 v[4:7], v[160:163], v[204:207], v[4:7]
	v_mfma_f32_16x16x32_bf16 v[0:3], v[168:171], v[204:207], v[0:3]
	s_setprio 0
	s_barrier
	s_add_i32 s55, 0, 0x18000
	s_add_i32 s56, 0, 0x1c000
	v_add_u32_e32 v152, s55, v138
	v_add_u32_e32 v168, s56, v138
	ds_read_b128 v[140:143], v152
	ds_read_b128 v[144:147], v152 offset:1024
	ds_read_b128 v[148:151], v152 offset:2048
	ds_read_b128 v[152:155], v152 offset:3072
	ds_read_b128 v[156:159], v168
	ds_read_b128 v[160:163], v168 offset:1024
	ds_read_b128 v[164:167], v168 offset:2048
	ds_read_b128 v[168:171], v168 offset:3072
	s_add_u32 s22, s22, 0x100000
	s_addc_u32 s23, s23, 0
	s_mov_b32 m0, s45
	ds_read_b128 v[172:175], v139 offset:32768
	ds_read_b128 v[176:179], v139 offset:33792
	ds_read_b128 v[184:187], v139 offset:34816
	ds_read_b128 v[188:191], v139 offset:35840
	ds_read_b128 v[192:195], v139 offset:36864
	ds_read_b128 v[196:199], v139 offset:37888
	ds_read_b128 v[200:203], v139 offset:38912
	ds_read_b128 v[204:207], v139 offset:39936
	global_load_lds_dwordx4 v132, s[22:23]
	s_mov_b32 m0, s46
	s_nop 0
	global_load_lds_dwordx4 v130, s[22:23]
	s_waitcnt vmcnt(8)
	s_waitcnt lgkmcnt(0)
	s_barrier
	s_setprio 1
	s_waitcnt lgkmcnt(0)
	v_mfma_f32_16x16x32_bf16 v[124:127], v[140:143], v[172:175], v[124:127]
	v_mfma_f32_16x16x32_bf16 v[120:123], v[148:151], v[172:175], v[120:123]
	v_mfma_f32_16x16x32_bf16 v[116:119], v[140:143], v[184:187], v[116:119]
	v_mfma_f32_16x16x32_bf16 v[112:115], v[148:151], v[184:187], v[112:115]
	v_mfma_f32_16x16x32_bf16 v[92:95], v[140:143], v[192:195], v[92:95]
	v_mfma_f32_16x16x32_bf16 v[88:91], v[148:151], v[192:195], v[88:91]
	v_mfma_f32_16x16x32_bf16 v[80:83], v[140:143], v[200:203], v[80:83]
	v_mfma_f32_16x16x32_bf16 v[72:75], v[148:151], v[200:203], v[72:75]
	v_mfma_f32_16x16x32_bf16 v[124:127], v[144:147], v[176:179], v[124:127]
	v_mfma_f32_16x16x32_bf16 v[120:123], v[152:155], v[176:179], v[120:123]
	v_mfma_f32_16x16x32_bf16 v[116:119], v[144:147], v[188:191], v[116:119]
	v_mfma_f32_16x16x32_bf16 v[112:115], v[152:155], v[188:191], v[112:115]
	v_mfma_f32_16x16x32_bf16 v[92:95], v[144:147], v[196:199], v[92:95]
	v_mfma_f32_16x16x32_bf16 v[88:91], v[152:155], v[196:199], v[88:91]
	v_mfma_f32_16x16x32_bf16 v[80:83], v[144:147], v[204:207], v[80:83]
	v_mfma_f32_16x16x32_bf16 v[72:75], v[152:155], v[204:207], v[72:75]
	s_setprio 0
	s_setprio 1
	v_mfma_f32_16x16x32_bf16 v[108:111], v[156:159], v[172:175], v[108:111]
	v_mfma_f32_16x16x32_bf16 v[104:107], v[164:167], v[172:175], v[104:107]
	v_mfma_f32_16x16x32_bf16 v[100:103], v[156:159], v[184:187], v[100:103]
	v_mfma_f32_16x16x32_bf16 v[96:99], v[164:167], v[184:187], v[96:99]
	v_mfma_f32_16x16x32_bf16 v[84:87], v[156:159], v[192:195], v[84:87]
	v_mfma_f32_16x16x32_bf16 v[76:79], v[164:167], v[192:195], v[76:79]
	v_mfma_f32_16x16x32_bf16 v[68:71], v[156:159], v[200:203], v[68:71]
	v_mfma_f32_16x16x32_bf16 v[64:67], v[164:167], v[200:203], v[64:67]
	v_mfma_f32_16x16x32_bf16 v[108:111], v[160:163], v[176:179], v[108:111]
	v_mfma_f32_16x16x32_bf16 v[104:107], v[168:171], v[176:179], v[104:107]
	v_mfma_f32_16x16x32_bf16 v[100:103], v[160:163], v[188:191], v[100:103]
	v_mfma_f32_16x16x32_bf16 v[96:99], v[168:171], v[188:191], v[96:99]
	v_mfma_f32_16x16x32_bf16 v[84:87], v[160:163], v[196:199], v[84:87]
	v_mfma_f32_16x16x32_bf16 v[76:79], v[168:171], v[196:199], v[76:79]
	v_mfma_f32_16x16x32_bf16 v[68:71], v[160:163], v[204:207], v[68:71]
	v_mfma_f32_16x16x32_bf16 v[64:67], v[168:171], v[204:207], v[64:67]
	s_setprio 0
	s_barrier
	s_add_i32 s22, s55, s42
	s_mov_b32 m0, s22
	ds_read_b128 v[172:175], v139 offset:49152
	ds_read_b128 v[176:179], v139 offset:50176
	ds_read_b128 v[184:187], v139 offset:51200
	ds_read_b128 v[188:191], v139 offset:52224
	ds_read_b128 v[192:195], v139 offset:53248
	ds_read_b128 v[196:199], v139 offset:54272
	ds_read_b128 v[200:203], v139 offset:55296
	ds_read_b128 v[204:207], v139 offset:56320
	global_load_lds_dwordx4 v212, s[84:85]
	s_add_i32 m0, s22, 0x2000
	s_add_u32 s20, s20, 0x100080
	s_addc_u32 s21, s21, 0
	s_add_i32 s22, s56, s42
	global_load_lds_dwordx4 v128, s[84:85]
	s_mov_b32 m0, s22
	s_nop 0
	global_load_lds_dwordx4 v212, s[20:21]
	s_add_i32 m0, s22, 0x2000
	s_nop 0
	global_load_lds_dwordx4 v128, s[20:21]
	s_mov_b32 m0, s48
	s_nop 0
	global_load_lds_dwordx4 v132, s[86:87]
	s_mov_b32 m0, s49
	s_nop 0
	global_load_lds_dwordx4 v130, s[86:87]
	s_waitcnt vmcnt(8)
	s_waitcnt lgkmcnt(0)
	s_barrier
	s_setprio 1
	s_waitcnt lgkmcnt(0)
	v_mfma_f32_16x16x32_bf16 v[60:63], v[140:143], v[172:175], v[60:63]
	v_mfma_f32_16x16x32_bf16 v[56:59], v[148:151], v[172:175], v[56:59]
	v_mfma_f32_16x16x32_bf16 v[48:51], v[140:143], v[184:187], v[48:51]
	v_mfma_f32_16x16x32_bf16 v[40:43], v[148:151], v[184:187], v[40:43]
	v_mfma_f32_16x16x32_bf16 v[28:31], v[140:143], v[192:195], v[28:31]
	v_mfma_f32_16x16x32_bf16 v[24:27], v[148:151], v[192:195], v[24:27]
	v_mfma_f32_16x16x32_bf16 v[16:19], v[140:143], v[200:203], v[16:19]
	v_mfma_f32_16x16x32_bf16 v[8:11], v[148:151], v[200:203], v[8:11]
	v_mfma_f32_16x16x32_bf16 v[60:63], v[144:147], v[176:179], v[60:63]
	v_mfma_f32_16x16x32_bf16 v[56:59], v[152:155], v[176:179], v[56:59]
	v_mfma_f32_16x16x32_bf16 v[48:51], v[144:147], v[188:191], v[48:51]
	v_mfma_f32_16x16x32_bf16 v[40:43], v[152:155], v[188:191], v[40:43]
	v_mfma_f32_16x16x32_bf16 v[28:31], v[144:147], v[196:199], v[28:31]
	v_mfma_f32_16x16x32_bf16 v[24:27], v[152:155], v[196:199], v[24:27]
	v_mfma_f32_16x16x32_bf16 v[16:19], v[144:147], v[204:207], v[16:19]
	v_mfma_f32_16x16x32_bf16 v[8:11], v[152:155], v[204:207], v[8:11]
	s_setprio 0
	s_setprio 1
	v_mfma_f32_16x16x32_bf16 v[52:55], v[156:159], v[172:175], v[52:55]
	v_mfma_f32_16x16x32_bf16 v[44:47], v[164:167], v[172:175], v[44:47]
	v_mfma_f32_16x16x32_bf16 v[36:39], v[156:159], v[184:187], v[36:39]
	v_mfma_f32_16x16x32_bf16 v[32:35], v[164:167], v[184:187], v[32:35]
	v_mfma_f32_16x16x32_bf16 v[20:23], v[156:159], v[192:195], v[20:23]
	v_mfma_f32_16x16x32_bf16 v[12:15], v[164:167], v[192:195], v[12:15]
	v_mfma_f32_16x16x32_bf16 v[4:7], v[156:159], v[200:203], v[4:7]
	v_mfma_f32_16x16x32_bf16 v[0:3], v[164:167], v[200:203], v[0:3]
	v_mfma_f32_16x16x32_bf16 v[52:55], v[160:163], v[176:179], v[52:55]
	v_mfma_f32_16x16x32_bf16 v[44:47], v[168:171], v[176:179], v[44:47]
	v_mfma_f32_16x16x32_bf16 v[36:39], v[160:163], v[188:191], v[36:39]
	v_mfma_f32_16x16x32_bf16 v[32:35], v[168:171], v[188:191], v[32:35]
	v_mfma_f32_16x16x32_bf16 v[20:23], v[160:163], v[196:199], v[20:23]
	v_mfma_f32_16x16x32_bf16 v[12:15], v[168:171], v[196:199], v[12:15]
	v_mfma_f32_16x16x32_bf16 v[4:7], v[160:163], v[204:207], v[4:7]
	v_mfma_f32_16x16x32_bf16 v[0:3], v[168:171], v[204:207], v[0:3]
	s_setprio 0
	s_barrier
	s_add_i32 s54, s54, 2
	s_add_u32 s18, s18, 0x100
	s_addc_u32 s19, s19, 0
	s_cmp_lt_u32 s54, 62
	s_cbranch_scc1 .LBB0_599
	s_waitcnt vmcnt(0)
	s_cmpk_gt_u32 s36, 0xff
	s_cbranch_scc1 .LBB0_602
	s_barrier
